# v114 plus ph2 conv-tap table copy with all six 16-byte loads per thread in flight before the LDS writes (was load, full wait, write per iteration)
# baseline (speedup 1.0000x reference)
; #define LAS __attribute__((address_space(3)))
; __device__ __forceinline__ void prep1_phase(const Frame& F, int l) {
;     ...
;     __syncthreads();
;     for (int i = F.tid; i < 3 * RWKV_COLS / 4; i += NTHREADS) *(LAS f32x4*)(cw + 4 * i) = *(const f32x4*)(conv + 4 * i);
;     __syncthreads();
.LBB0_374:
	s_movk_i32 s8, 0x8df
	s_mov_b64 s[24:25], 0
	s_mov_b64 s[26:27], 0
	s_mov_b64 s[28:29], 0
	s_mov_b64 s[30:31], 0
	s_mov_b64 s[36:37], 0
	s_mov_b64 s[38:39], 0
	s_mov_b64 s[24:25], exec
	v_ashrrev_i32_e32 v7, 31, v6
	v_lshl_add_u64 v[240:241], v[6:7], 2, s[4:5]
	global_load_dwordx4 v[152:155], v[240:241], off
	v_add_u32_e32 v5, 0x200, v5
	v_add_u32_e32 v6, 0x800, v6
	v_cmp_ge_i32_e32 vcc, s8, v5
	s_and_b64 exec, exec, vcc
	s_cbranch_execz .Lmy_ct_ld_done
	s_mov_b64 s[26:27], exec
	v_ashrrev_i32_e32 v7, 31, v6
	v_lshl_add_u64 v[240:241], v[6:7], 2, s[4:5]
	global_load_dwordx4 v[156:159], v[240:241], off
	v_add_u32_e32 v5, 0x200, v5
	v_add_u32_e32 v6, 0x800, v6
	v_cmp_ge_i32_e32 vcc, s8, v5
	s_and_b64 exec, exec, vcc
	s_cbranch_execz .Lmy_ct_ld_done
	s_mov_b64 s[28:29], exec
	v_ashrrev_i32_e32 v7, 31, v6
	v_lshl_add_u64 v[240:241], v[6:7], 2, s[4:5]
	global_load_dwordx4 v[160:163], v[240:241], off
	v_add_u32_e32 v5, 0x200, v5
	v_add_u32_e32 v6, 0x800, v6
	v_cmp_ge_i32_e32 vcc, s8, v5
	s_and_b64 exec, exec, vcc
	s_cbranch_execz .Lmy_ct_ld_done
	s_mov_b64 s[30:31], exec
	v_ashrrev_i32_e32 v7, 31, v6
	v_lshl_add_u64 v[240:241], v[6:7], 2, s[4:5]
	global_load_dwordx4 v[164:167], v[240:241], off
	v_add_u32_e32 v5, 0x200, v5
	v_add_u32_e32 v6, 0x800, v6
	v_cmp_ge_i32_e32 vcc, s8, v5
	s_and_b64 exec, exec, vcc
	s_cbranch_execz .Lmy_ct_ld_done
	s_mov_b64 s[36:37], exec
	v_ashrrev_i32_e32 v7, 31, v6
	v_lshl_add_u64 v[240:241], v[6:7], 2, s[4:5]
	global_load_dwordx4 v[232:235], v[240:241], off
	v_add_u32_e32 v5, 0x200, v5
	v_add_u32_e32 v6, 0x800, v6
	v_cmp_ge_i32_e32 vcc, s8, v5
	s_and_b64 exec, exec, vcc
	s_cbranch_execz .Lmy_ct_ld_done
	s_mov_b64 s[38:39], exec
	v_ashrrev_i32_e32 v7, 31, v6
	v_lshl_add_u64 v[240:241], v[6:7], 2, s[4:5]
	global_load_dwordx4 v[236:239], v[240:241], off
	v_add_u32_e32 v5, 0x200, v5
	v_add_u32_e32 v6, 0x800, v6
	v_cmp_ge_i32_e32 vcc, s8, v5
	s_and_b64 exec, exec, vcc
.Lmy_ct_ld_done:
	s_mov_b64 s[6:7], exec
	s_waitcnt vmcnt(0)
	s_mov_b64 exec, s[24:25]
	ds_write_b128 v9, v[152:155]
	s_mov_b64 exec, s[26:27]
	s_cbranch_execz .Lmy_ct_st_done
	ds_write_b128 v9, v[156:159] offset:8192
	s_mov_b64 exec, s[28:29]
	s_cbranch_execz .Lmy_ct_st_done
	ds_write_b128 v9, v[160:163] offset:16384
	s_mov_b64 exec, s[30:31]
	s_cbranch_execz .Lmy_ct_st_done
	ds_write_b128 v9, v[164:167] offset:24576
	s_mov_b64 exec, s[36:37]
	s_cbranch_execz .Lmy_ct_st_done
	ds_write_b128 v9, v[232:235] offset:32768
	s_mov_b64 exec, s[38:39]
	s_cbranch_execz .Lmy_ct_st_done
	ds_write_b128 v9, v[236:239] offset:40960
.Lmy_ct_st_done:
	s_mov_b64 exec, s[6:7]
	v_add_u32_e32 v9, 0xc000, v9
	s_cbranch_execnz .LBB0_374
